# S5 pass 2: carry-in loop loads (up to 15 serialized round trips) all requested up front, recurrence unrolled with counted waits
# speedup vs baseline: 1.0155x; 1.0155x over previous
.LBB0_181:
	s_mov_b64 s[12:13], 0x6000
	global_load_dword v126, v[4:5], off offset:-256
	global_load_dword v129, v[4:5], off offset:128
	global_load_dword v127, v[4:5], off offset:-128
	global_load_dword v128, v[4:5], off
	v_lshl_add_u64 v[4:5], v[4:5], 0, s[12:13]
	global_load_dword v130, v[4:5], off offset:-256
	global_load_dword v133, v[4:5], off offset:128
	global_load_dword v131, v[4:5], off offset:-128
	global_load_dword v132, v[4:5], off
	v_lshl_add_u64 v[4:5], v[4:5], 0, s[12:13]
	global_load_dword v134, v[4:5], off offset:-256
	global_load_dword v137, v[4:5], off offset:128
	global_load_dword v135, v[4:5], off offset:-128
	global_load_dword v136, v[4:5], off
	v_lshl_add_u64 v[4:5], v[4:5], 0, s[12:13]
	global_load_dword v138, v[4:5], off offset:-256
	global_load_dword v141, v[4:5], off offset:128
	global_load_dword v139, v[4:5], off offset:-128
	global_load_dword v140, v[4:5], off
	v_lshl_add_u64 v[4:5], v[4:5], 0, s[12:13]
	global_load_dword v142, v[4:5], off offset:-256
	global_load_dword v145, v[4:5], off offset:128
	global_load_dword v143, v[4:5], off offset:-128
	global_load_dword v144, v[4:5], off
	v_lshl_add_u64 v[4:5], v[4:5], 0, s[12:13]
	global_load_dword v146, v[4:5], off offset:-256
	global_load_dword v149, v[4:5], off offset:128
	global_load_dword v147, v[4:5], off offset:-128
	global_load_dword v148, v[4:5], off
	v_lshl_add_u64 v[4:5], v[4:5], 0, s[12:13]
	global_load_dword v150, v[4:5], off offset:-256
	global_load_dword v153, v[4:5], off offset:128
	global_load_dword v151, v[4:5], off offset:-128
	global_load_dword v152, v[4:5], off
	v_lshl_add_u64 v[4:5], v[4:5], 0, s[12:13]
	global_load_dword v154, v[4:5], off offset:-256
	global_load_dword v157, v[4:5], off offset:128
	global_load_dword v155, v[4:5], off offset:-128
	global_load_dword v156, v[4:5], off
	v_lshl_add_u64 v[4:5], v[4:5], 0, s[12:13]
	global_load_dword v170, v[4:5], off offset:-256
	global_load_dword v173, v[4:5], off offset:128
	global_load_dword v171, v[4:5], off offset:-128
	global_load_dword v172, v[4:5], off
	v_lshl_add_u64 v[4:5], v[4:5], 0, s[12:13]
	global_load_dword v174, v[4:5], off offset:-256
	global_load_dword v177, v[4:5], off offset:128
	global_load_dword v175, v[4:5], off offset:-128
	global_load_dword v176, v[4:5], off
	v_lshl_add_u64 v[4:5], v[4:5], 0, s[12:13]
	global_load_dword v178, v[4:5], off offset:-256
	global_load_dword v181, v[4:5], off offset:128
	global_load_dword v179, v[4:5], off offset:-128
	global_load_dword v180, v[4:5], off
	v_lshl_add_u64 v[4:5], v[4:5], 0, s[12:13]
	global_load_dword v182, v[4:5], off offset:-256
	global_load_dword v185, v[4:5], off offset:128
	global_load_dword v183, v[4:5], off offset:-128
	global_load_dword v184, v[4:5], off
	v_lshl_add_u64 v[4:5], v[4:5], 0, s[12:13]
	global_load_dword v186, v[4:5], off offset:-256
	global_load_dword v189, v[4:5], off offset:128
	global_load_dword v187, v[4:5], off offset:-128
	global_load_dword v188, v[4:5], off
	v_lshl_add_u64 v[4:5], v[4:5], 0, s[12:13]
	global_load_dword v190, v[4:5], off offset:-256
	global_load_dword v193, v[4:5], off offset:128
	global_load_dword v191, v[4:5], off offset:-128
	global_load_dword v192, v[4:5], off
	v_lshl_add_u64 v[4:5], v[4:5], 0, s[12:13]
	global_load_dword v6, v[4:5], off offset:-256
	global_load_dword v9, v[4:5], off offset:128
	global_load_dword v7, v[4:5], off offset:-128
	global_load_dword v8, v[4:5], off
	v_pk_mul_f32 v[10:11], v[2:3], v[196:197]
	v_pk_mul_f32 v[12:13], v[2:3], v[198:199]
	v_pk_fma_f32 v[10:11], v[0:1], v[198:199], v[10:11] neg_lo:[0,0,1] neg_hi:[0,0,1]
	v_pk_fma_f32 v[12:13], v[0:1], v[196:197], v[12:13]
	s_waitcnt vmcnt(56)
	v_pk_add_f32 v[198:199], v[10:11], v[126:127]
	v_pk_add_f32 v[196:197], v[12:13], v[128:129]
	s_cmp_eq_u32 s11, 1
	s_cbranch_scc1 .LBB0_183
	v_pk_mul_f32 v[10:11], v[2:3], v[196:197]
	v_pk_mul_f32 v[12:13], v[2:3], v[198:199]
	v_pk_fma_f32 v[10:11], v[0:1], v[198:199], v[10:11] neg_lo:[0,0,1] neg_hi:[0,0,1]
	v_pk_fma_f32 v[12:13], v[0:1], v[196:197], v[12:13]
	s_waitcnt vmcnt(52)
	v_pk_add_f32 v[198:199], v[10:11], v[130:131]
	v_pk_add_f32 v[196:197], v[12:13], v[132:133]
	s_cmp_eq_u32 s11, 2
	s_cbranch_scc1 .LBB0_183
	v_pk_mul_f32 v[10:11], v[2:3], v[196:197]
	v_pk_mul_f32 v[12:13], v[2:3], v[198:199]
	v_pk_fma_f32 v[10:11], v[0:1], v[198:199], v[10:11] neg_lo:[0,0,1] neg_hi:[0,0,1]
	v_pk_fma_f32 v[12:13], v[0:1], v[196:197], v[12:13]
	s_waitcnt vmcnt(48)
	v_pk_add_f32 v[198:199], v[10:11], v[134:135]
	v_pk_add_f32 v[196:197], v[12:13], v[136:137]
	s_cmp_eq_u32 s11, 3
	s_cbranch_scc1 .LBB0_183
	v_pk_mul_f32 v[10:11], v[2:3], v[196:197]
	v_pk_mul_f32 v[12:13], v[2:3], v[198:199]
	v_pk_fma_f32 v[10:11], v[0:1], v[198:199], v[10:11] neg_lo:[0,0,1] neg_hi:[0,0,1]
	v_pk_fma_f32 v[12:13], v[0:1], v[196:197], v[12:13]
	s_waitcnt vmcnt(44)
	v_pk_add_f32 v[198:199], v[10:11], v[138:139]
	v_pk_add_f32 v[196:197], v[12:13], v[140:141]
	s_cmp_eq_u32 s11, 4
	s_cbranch_scc1 .LBB0_183
	v_pk_mul_f32 v[10:11], v[2:3], v[196:197]
	v_pk_mul_f32 v[12:13], v[2:3], v[198:199]
	v_pk_fma_f32 v[10:11], v[0:1], v[198:199], v[10:11] neg_lo:[0,0,1] neg_hi:[0,0,1]
	v_pk_fma_f32 v[12:13], v[0:1], v[196:197], v[12:13]
	s_waitcnt vmcnt(40)
	v_pk_add_f32 v[198:199], v[10:11], v[142:143]
	v_pk_add_f32 v[196:197], v[12:13], v[144:145]
	s_cmp_eq_u32 s11, 5
	s_cbranch_scc1 .LBB0_183
	v_pk_mul_f32 v[10:11], v[2:3], v[196:197]
	v_pk_mul_f32 v[12:13], v[2:3], v[198:199]
	v_pk_fma_f32 v[10:11], v[0:1], v[198:199], v[10:11] neg_lo:[0,0,1] neg_hi:[0,0,1]
	v_pk_fma_f32 v[12:13], v[0:1], v[196:197], v[12:13]
	s_waitcnt vmcnt(36)
	v_pk_add_f32 v[198:199], v[10:11], v[146:147]
	v_pk_add_f32 v[196:197], v[12:13], v[148:149]
	s_cmp_eq_u32 s11, 6
	s_cbranch_scc1 .LBB0_183
	v_pk_mul_f32 v[10:11], v[2:3], v[196:197]
	v_pk_mul_f32 v[12:13], v[2:3], v[198:199]
	v_pk_fma_f32 v[10:11], v[0:1], v[198:199], v[10:11] neg_lo:[0,0,1] neg_hi:[0,0,1]
	v_pk_fma_f32 v[12:13], v[0:1], v[196:197], v[12:13]
	s_waitcnt vmcnt(32)
	v_pk_add_f32 v[198:199], v[10:11], v[150:151]
	v_pk_add_f32 v[196:197], v[12:13], v[152:153]
	s_cmp_eq_u32 s11, 7
	s_cbranch_scc1 .LBB0_183
	v_pk_mul_f32 v[10:11], v[2:3], v[196:197]
	v_pk_mul_f32 v[12:13], v[2:3], v[198:199]
	v_pk_fma_f32 v[10:11], v[0:1], v[198:199], v[10:11] neg_lo:[0,0,1] neg_hi:[0,0,1]
	v_pk_fma_f32 v[12:13], v[0:1], v[196:197], v[12:13]
	s_waitcnt vmcnt(28)
	v_pk_add_f32 v[198:199], v[10:11], v[154:155]
	v_pk_add_f32 v[196:197], v[12:13], v[156:157]
	s_cmp_eq_u32 s11, 8
	s_cbranch_scc1 .LBB0_183
	v_pk_mul_f32 v[10:11], v[2:3], v[196:197]
	v_pk_mul_f32 v[12:13], v[2:3], v[198:199]
	v_pk_fma_f32 v[10:11], v[0:1], v[198:199], v[10:11] neg_lo:[0,0,1] neg_hi:[0,0,1]
	v_pk_fma_f32 v[12:13], v[0:1], v[196:197], v[12:13]
	s_waitcnt vmcnt(24)
	v_pk_add_f32 v[198:199], v[10:11], v[170:171]
	v_pk_add_f32 v[196:197], v[12:13], v[172:173]
	s_cmp_eq_u32 s11, 9
	s_cbranch_scc1 .LBB0_183
	v_pk_mul_f32 v[10:11], v[2:3], v[196:197]
	v_pk_mul_f32 v[12:13], v[2:3], v[198:199]
	v_pk_fma_f32 v[10:11], v[0:1], v[198:199], v[10:11] neg_lo:[0,0,1] neg_hi:[0,0,1]
	v_pk_fma_f32 v[12:13], v[0:1], v[196:197], v[12:13]
	s_waitcnt vmcnt(20)
	v_pk_add_f32 v[198:199], v[10:11], v[174:175]
	v_pk_add_f32 v[196:197], v[12:13], v[176:177]
	s_cmp_eq_u32 s11, 10
	s_cbranch_scc1 .LBB0_183
	v_pk_mul_f32 v[10:11], v[2:3], v[196:197]
	v_pk_mul_f32 v[12:13], v[2:3], v[198:199]
	v_pk_fma_f32 v[10:11], v[0:1], v[198:199], v[10:11] neg_lo:[0,0,1] neg_hi:[0,0,1]
	v_pk_fma_f32 v[12:13], v[0:1], v[196:197], v[12:13]
	s_waitcnt vmcnt(16)
	v_pk_add_f32 v[198:199], v[10:11], v[178:179]
	v_pk_add_f32 v[196:197], v[12:13], v[180:181]
	s_cmp_eq_u32 s11, 11
	s_cbranch_scc1 .LBB0_183
	v_pk_mul_f32 v[10:11], v[2:3], v[196:197]
	v_pk_mul_f32 v[12:13], v[2:3], v[198:199]
	v_pk_fma_f32 v[10:11], v[0:1], v[198:199], v[10:11] neg_lo:[0,0,1] neg_hi:[0,0,1]
	v_pk_fma_f32 v[12:13], v[0:1], v[196:197], v[12:13]
	s_waitcnt vmcnt(12)
	v_pk_add_f32 v[198:199], v[10:11], v[182:183]
	v_pk_add_f32 v[196:197], v[12:13], v[184:185]
	s_cmp_eq_u32 s11, 12
	s_cbranch_scc1 .LBB0_183
	v_pk_mul_f32 v[10:11], v[2:3], v[196:197]
	v_pk_mul_f32 v[12:13], v[2:3], v[198:199]
	v_pk_fma_f32 v[10:11], v[0:1], v[198:199], v[10:11] neg_lo:[0,0,1] neg_hi:[0,0,1]
	v_pk_fma_f32 v[12:13], v[0:1], v[196:197], v[12:13]
	s_waitcnt vmcnt(8)
	v_pk_add_f32 v[198:199], v[10:11], v[186:187]
	v_pk_add_f32 v[196:197], v[12:13], v[188:189]
	s_cmp_eq_u32 s11, 13
	s_cbranch_scc1 .LBB0_183
	v_pk_mul_f32 v[10:11], v[2:3], v[196:197]
	v_pk_mul_f32 v[12:13], v[2:3], v[198:199]
	v_pk_fma_f32 v[10:11], v[0:1], v[198:199], v[10:11] neg_lo:[0,0,1] neg_hi:[0,0,1]
	v_pk_fma_f32 v[12:13], v[0:1], v[196:197], v[12:13]
	s_waitcnt vmcnt(4)
	v_pk_add_f32 v[198:199], v[10:11], v[190:191]
	v_pk_add_f32 v[196:197], v[12:13], v[192:193]
	s_cmp_eq_u32 s11, 14
	s_cbranch_scc1 .LBB0_183
	v_pk_mul_f32 v[10:11], v[2:3], v[196:197]
	v_pk_mul_f32 v[12:13], v[2:3], v[198:199]
	v_pk_fma_f32 v[10:11], v[0:1], v[198:199], v[10:11] neg_lo:[0,0,1] neg_hi:[0,0,1]
	v_pk_fma_f32 v[12:13], v[0:1], v[196:197], v[12:13]
	s_waitcnt vmcnt(0)
	v_pk_add_f32 v[198:199], v[10:11], v[6:7]
	v_pk_add_f32 v[196:197], v[12:13], v[8:9]
	s_branch .LBB0_183
